# single edit edit_scan_inner
# baseline (speedup 1.0000x reference)
.LBB0_1010:
	s_mov_b64 s[78:79], -1
	s_and_b64 vcc, exec, s[70:71]
	s_cbranch_vccz .LBB0_1014
	s_setprio 1
	s_and_b32 s55, s53, 1
	s_lshl_b32 s56, s55, 14
	s_mul_i32 s55, s55, 0xaa00
	v_or_b32_e32 v99, s56, v143
	v_lshl_add_u32 v96, v106, 2, s55
	v_lshl_add_u32 v97, v101, 2, s55
	v_mov_b32_e32 v98, s55
	v_add_u32_e32 v99, 0x15400, v99
	s_waitcnt vmcnt(0)
	ds_read_b128 v[170:173], v96 offset:256
	ds_read_b128 v[174:177], v96 offset:512
	ds_read_b128 v[166:169], v96
	ds_read_b128 v[182:185], v96 offset:1024
	ds_read_b128 v[178:181], v96 offset:768
	ds_read_b32 v186, v97 offset:1280
	ds_read_b64 v[188:189], v98 offset:1344
	ds_read_b128 v[194:197], v96 offset:1616
	ds_read_b128 v[198:201], v96 offset:1872
	ds_read_b128 v[190:193], v96 offset:1360
	ds_read_b128 v[206:209], v96 offset:2384
	ds_read_b128 v[202:205], v96 offset:2128
	ds_read_b32 v210, v97 offset:2640
	ds_read_b64 v[220:221], v98 offset:2704
	v_mov_b64_e32 v[48:49], v[92:93]
	v_mov_b64_e32 v[52:53], v[94:95]
	s_waitcnt lgkmcnt(7)
	v_pk_mul_f32 v[58:59], v[52:53], v[170:171] op_sel_hi:[0,1]
	ds_read_b128 v[32:35], v96 offset:2976
	v_pk_fma_f32 v[58:59], v[52:53], v[172:173], v[58:59] op_sel:[1,0,0]
	ds_read_b128 v[36:39], v96 offset:3232
	v_pk_fma_f32 v[58:59], v[48:49], v[174:175], v[58:59] op_sel_hi:[0,1,1]
	v_pk_mul_f32 v[64:65], v[186:187], v[182:183] op_sel_hi:[0,1]
	v_pk_fma_f32 v[58:59], v[48:49], v[176:177], v[58:59] op_sel:[1,0,0]
	v_pk_mul_f32 v[66:67], v[186:187], v[184:185] op_sel_hi:[0,1]
	v_pk_fma_f32 v[64:65], v[52:53], v[166:167], v[64:65]
	v_add_f32_dpp v58, v58, v58 row_ror:8 row_mask:0xf bank_mask:0xf bound_ctrl:1
	v_pk_fma_f32 v[66:67], v[48:49], v[168:169], v[66:67]
	v_add_f32_dpp v60, v59, v59 row_ror:8 row_mask:0xf bank_mask:0xf bound_ctrl:1
	v_add_f32_dpp v58, v58, v58 row_ror:4 row_mask:0xf bank_mask:0xf bound_ctrl:1
	ds_read_b128 v[28:31], v96 offset:2720
	ds_read_b128 v[44:47], v96 offset:3744
	v_add_f32_dpp v58, v58, v58 row_ror:2 row_mask:0xf bank_mask:0xf bound_ctrl:1
	ds_read_b128 v[40:43], v96 offset:3488
	v_fma_f32 v61, v186, v189, v60
	v_add_f32_dpp v58, v58, v58 row_ror:1 row_mask:0xf bank_mask:0xf bound_ctrl:1
	v_pk_fma_f32 v[52:53], v[58:59], v[178:179], v[64:65] op_sel_hi:[0,1,1]
	v_pk_fma_f32 v[48:49], v[58:59], v[180:181], v[66:67] op_sel_hi:[0,1,1]
	v_fma_f32 v61, v58, v188, v61
	ds_read_b32 v54, v97 offset:4000
	ds_read_b64 v[56:57], v98 offset:4064
	ds_write_b32 v99, v61
	s_waitcnt lgkmcnt(8)
	v_pk_mul_f32 v[58:59], v[52:53], v[194:195] op_sel_hi:[0,1]
	ds_read_b128 v[170:173], v96 offset:4336
	v_pk_fma_f32 v[58:59], v[52:53], v[196:197], v[58:59] op_sel:[1,0,0]
	ds_read_b128 v[174:177], v96 offset:4592
	v_pk_fma_f32 v[58:59], v[48:49], v[198:199], v[58:59] op_sel_hi:[0,1,1]
	v_pk_mul_f32 v[64:65], v[210:211], v[206:207] op_sel_hi:[0,1]
	v_pk_fma_f32 v[58:59], v[48:49], v[200:201], v[58:59] op_sel:[1,0,0]
	v_pk_mul_f32 v[66:67], v[210:211], v[208:209] op_sel_hi:[0,1]
	v_pk_fma_f32 v[64:65], v[52:53], v[190:191], v[64:65]
	v_add_f32_dpp v58, v58, v58 row_ror:8 row_mask:0xf bank_mask:0xf bound_ctrl:1
	v_pk_fma_f32 v[66:67], v[48:49], v[192:193], v[66:67]
	v_add_f32_dpp v60, v59, v59 row_ror:8 row_mask:0xf bank_mask:0xf bound_ctrl:1
	v_add_f32_dpp v58, v58, v58 row_ror:4 row_mask:0xf bank_mask:0xf bound_ctrl:1
	ds_read_b128 v[166:169], v96 offset:4080
	ds_read_b128 v[182:185], v96 offset:5104
	v_add_f32_dpp v58, v58, v58 row_ror:2 row_mask:0xf bank_mask:0xf bound_ctrl:1
	ds_read_b128 v[178:181], v96 offset:4848
	v_fma_f32 v61, v210, v221, v60
	v_add_f32_dpp v58, v58, v58 row_ror:1 row_mask:0xf bank_mask:0xf bound_ctrl:1
	v_pk_fma_f32 v[52:53], v[58:59], v[202:203], v[64:65] op_sel_hi:[0,1,1]
	v_pk_fma_f32 v[48:49], v[58:59], v[204:205], v[66:67] op_sel_hi:[0,1,1]
	v_fma_f32 v61, v58, v220, v61
	ds_read_b32 v186, v97 offset:5360
	ds_read_b64 v[188:189], v98 offset:5424
	ds_write_b32 v99, v61 offset:512
	s_waitcnt lgkmcnt(9)
	v_pk_mul_f32 v[58:59], v[52:53], v[32:33] op_sel_hi:[0,1]
	ds_read_b128 v[194:197], v96 offset:5696
	v_pk_fma_f32 v[58:59], v[52:53], v[34:35], v[58:59] op_sel:[1,0,0]
	ds_read_b128 v[198:201], v96 offset:5952
	v_pk_fma_f32 v[58:59], v[48:49], v[36:37], v[58:59] op_sel_hi:[0,1,1]
	v_pk_mul_f32 v[64:65], v[54:55], v[44:45] op_sel_hi:[0,1]
	v_pk_fma_f32 v[58:59], v[48:49], v[38:39], v[58:59] op_sel:[1,0,0]
	v_pk_mul_f32 v[66:67], v[54:55], v[46:47] op_sel_hi:[0,1]
	v_pk_fma_f32 v[64:65], v[52:53], v[28:29], v[64:65]
	v_add_f32_dpp v58, v58, v58 row_ror:8 row_mask:0xf bank_mask:0xf bound_ctrl:1
	v_pk_fma_f32 v[66:67], v[48:49], v[30:31], v[66:67]
	v_add_f32_dpp v60, v59, v59 row_ror:8 row_mask:0xf bank_mask:0xf bound_ctrl:1
	v_add_f32_dpp v58, v58, v58 row_ror:4 row_mask:0xf bank_mask:0xf bound_ctrl:1
	ds_read_b128 v[190:193], v96 offset:5440
	ds_read_b128 v[206:209], v96 offset:6464
	v_add_f32_dpp v58, v58, v58 row_ror:2 row_mask:0xf bank_mask:0xf bound_ctrl:1
	ds_read_b128 v[202:205], v96 offset:6208
	v_fma_f32 v61, v54, v57, v60
	v_add_f32_dpp v58, v58, v58 row_ror:1 row_mask:0xf bank_mask:0xf bound_ctrl:1
	v_pk_fma_f32 v[52:53], v[58:59], v[40:41], v[64:65] op_sel_hi:[0,1,1]
	v_pk_fma_f32 v[48:49], v[58:59], v[42:43], v[66:67] op_sel_hi:[0,1,1]
	v_fma_f32 v61, v58, v56, v61
	ds_read_b32 v210, v97 offset:6720
	ds_read_b64 v[220:221], v98 offset:6784
	ds_write_b32 v99, v61 offset:1024
	s_waitcnt lgkmcnt(9)
	v_pk_mul_f32 v[58:59], v[52:53], v[170:171] op_sel_hi:[0,1]
	ds_read_b128 v[32:35], v96 offset:7056
	v_pk_fma_f32 v[58:59], v[52:53], v[172:173], v[58:59] op_sel:[1,0,0]
	ds_read_b128 v[36:39], v96 offset:7312
	v_pk_fma_f32 v[58:59], v[48:49], v[174:175], v[58:59] op_sel_hi:[0,1,1]
	v_pk_mul_f32 v[64:65], v[186:187], v[182:183] op_sel_hi:[0,1]
	v_pk_fma_f32 v[58:59], v[48:49], v[176:177], v[58:59] op_sel:[1,0,0]
	v_pk_mul_f32 v[66:67], v[186:187], v[184:185] op_sel_hi:[0,1]
	v_pk_fma_f32 v[64:65], v[52:53], v[166:167], v[64:65]
	v_add_f32_dpp v58, v58, v58 row_ror:8 row_mask:0xf bank_mask:0xf bound_ctrl:1
	v_pk_fma_f32 v[66:67], v[48:49], v[168:169], v[66:67]
	v_add_f32_dpp v60, v59, v59 row_ror:8 row_mask:0xf bank_mask:0xf bound_ctrl:1
	v_add_f32_dpp v58, v58, v58 row_ror:4 row_mask:0xf bank_mask:0xf bound_ctrl:1
	ds_read_b128 v[28:31], v96 offset:6800
	ds_read_b128 v[44:47], v96 offset:7824
	v_add_f32_dpp v58, v58, v58 row_ror:2 row_mask:0xf bank_mask:0xf bound_ctrl:1
	ds_read_b128 v[40:43], v96 offset:7568
	v_fma_f32 v61, v186, v189, v60
	v_add_f32_dpp v58, v58, v58 row_ror:1 row_mask:0xf bank_mask:0xf bound_ctrl:1
	v_pk_fma_f32 v[52:53], v[58:59], v[178:179], v[64:65] op_sel_hi:[0,1,1]
	v_pk_fma_f32 v[48:49], v[58:59], v[180:181], v[66:67] op_sel_hi:[0,1,1]
	v_fma_f32 v61, v58, v188, v61
	ds_read_b32 v54, v97 offset:8080
	ds_read_b64 v[56:57], v98 offset:8144
	ds_write_b32 v99, v61 offset:1536
	s_waitcnt lgkmcnt(9)
	v_pk_mul_f32 v[58:59], v[52:53], v[194:195] op_sel_hi:[0,1]
	ds_read_b128 v[170:173], v96 offset:8416
	v_pk_fma_f32 v[58:59], v[52:53], v[196:197], v[58:59] op_sel:[1,0,0]
	ds_read_b128 v[174:177], v96 offset:8672
	v_pk_fma_f32 v[58:59], v[48:49], v[198:199], v[58:59] op_sel_hi:[0,1,1]
	v_pk_mul_f32 v[64:65], v[210:211], v[206:207] op_sel_hi:[0,1]
	v_pk_fma_f32 v[58:59], v[48:49], v[200:201], v[58:59] op_sel:[1,0,0]
	v_pk_mul_f32 v[66:67], v[210:211], v[208:209] op_sel_hi:[0,1]
	v_pk_fma_f32 v[64:65], v[52:53], v[190:191], v[64:65]
	v_add_f32_dpp v58, v58, v58 row_ror:8 row_mask:0xf bank_mask:0xf bound_ctrl:1
	v_pk_fma_f32 v[66:67], v[48:49], v[192:193], v[66:67]
	v_add_f32_dpp v60, v59, v59 row_ror:8 row_mask:0xf bank_mask:0xf bound_ctrl:1
	v_add_f32_dpp v58, v58, v58 row_ror:4 row_mask:0xf bank_mask:0xf bound_ctrl:1
	ds_read_b128 v[166:169], v96 offset:8160
	ds_read_b128 v[182:185], v96 offset:9184
	v_add_f32_dpp v58, v58, v58 row_ror:2 row_mask:0xf bank_mask:0xf bound_ctrl:1
	ds_read_b128 v[178:181], v96 offset:8928
	v_fma_f32 v61, v210, v221, v60
	v_add_f32_dpp v58, v58, v58 row_ror:1 row_mask:0xf bank_mask:0xf bound_ctrl:1
	v_pk_fma_f32 v[52:53], v[58:59], v[202:203], v[64:65] op_sel_hi:[0,1,1]
	v_pk_fma_f32 v[48:49], v[58:59], v[204:205], v[66:67] op_sel_hi:[0,1,1]
	v_fma_f32 v61, v58, v220, v61
	ds_read_b32 v186, v97 offset:9440
	ds_read_b64 v[188:189], v98 offset:9504
	ds_write_b32 v99, v61 offset:2048
	s_waitcnt lgkmcnt(9)
	v_pk_mul_f32 v[58:59], v[52:53], v[32:33] op_sel_hi:[0,1]
	ds_read_b128 v[194:197], v96 offset:9776
	v_pk_fma_f32 v[58:59], v[52:53], v[34:35], v[58:59] op_sel:[1,0,0]
	ds_read_b128 v[198:201], v96 offset:10032
	v_pk_fma_f32 v[58:59], v[48:49], v[36:37], v[58:59] op_sel_hi:[0,1,1]
	v_pk_mul_f32 v[64:65], v[54:55], v[44:45] op_sel_hi:[0,1]
	v_pk_fma_f32 v[58:59], v[48:49], v[38:39], v[58:59] op_sel:[1,0,0]
	v_pk_mul_f32 v[66:67], v[54:55], v[46:47] op_sel_hi:[0,1]
	v_pk_fma_f32 v[64:65], v[52:53], v[28:29], v[64:65]
	v_add_f32_dpp v58, v58, v58 row_ror:8 row_mask:0xf bank_mask:0xf bound_ctrl:1
	v_pk_fma_f32 v[66:67], v[48:49], v[30:31], v[66:67]
	v_add_f32_dpp v60, v59, v59 row_ror:8 row_mask:0xf bank_mask:0xf bound_ctrl:1
	v_add_f32_dpp v58, v58, v58 row_ror:4 row_mask:0xf bank_mask:0xf bound_ctrl:1
	ds_read_b128 v[190:193], v96 offset:9520
	ds_read_b128 v[206:209], v96 offset:10544
	v_add_f32_dpp v58, v58, v58 row_ror:2 row_mask:0xf bank_mask:0xf bound_ctrl:1
	ds_read_b128 v[202:205], v96 offset:10288
	v_fma_f32 v61, v54, v57, v60
	v_add_f32_dpp v58, v58, v58 row_ror:1 row_mask:0xf bank_mask:0xf bound_ctrl:1
	v_pk_fma_f32 v[52:53], v[58:59], v[40:41], v[64:65] op_sel_hi:[0,1,1]
	v_pk_fma_f32 v[48:49], v[58:59], v[42:43], v[66:67] op_sel_hi:[0,1,1]
	v_fma_f32 v61, v58, v56, v61
	ds_read_b32 v210, v97 offset:10800
	ds_read_b64 v[220:221], v98 offset:10864
	ds_write_b32 v99, v61 offset:2560
	s_waitcnt lgkmcnt(9)
	v_pk_mul_f32 v[58:59], v[52:53], v[170:171] op_sel_hi:[0,1]
	ds_read_b128 v[32:35], v96 offset:11136
	v_pk_fma_f32 v[58:59], v[52:53], v[172:173], v[58:59] op_sel:[1,0,0]
	ds_read_b128 v[36:39], v96 offset:11392
	v_pk_fma_f32 v[58:59], v[48:49], v[174:175], v[58:59] op_sel_hi:[0,1,1]
	v_pk_mul_f32 v[64:65], v[186:187], v[182:183] op_sel_hi:[0,1]
	v_pk_fma_f32 v[58:59], v[48:49], v[176:177], v[58:59] op_sel:[1,0,0]
	v_pk_mul_f32 v[66:67], v[186:187], v[184:185] op_sel_hi:[0,1]
	v_pk_fma_f32 v[64:65], v[52:53], v[166:167], v[64:65]
	v_add_f32_dpp v58, v58, v58 row_ror:8 row_mask:0xf bank_mask:0xf bound_ctrl:1
	v_pk_fma_f32 v[66:67], v[48:49], v[168:169], v[66:67]
	v_add_f32_dpp v60, v59, v59 row_ror:8 row_mask:0xf bank_mask:0xf bound_ctrl:1
	v_add_f32_dpp v58, v58, v58 row_ror:4 row_mask:0xf bank_mask:0xf bound_ctrl:1
	ds_read_b128 v[28:31], v96 offset:10880
	ds_read_b128 v[44:47], v96 offset:11904
	v_add_f32_dpp v58, v58, v58 row_ror:2 row_mask:0xf bank_mask:0xf bound_ctrl:1
	ds_read_b128 v[40:43], v96 offset:11648
	v_fma_f32 v61, v186, v189, v60
	v_add_f32_dpp v58, v58, v58 row_ror:1 row_mask:0xf bank_mask:0xf bound_ctrl:1
	v_pk_fma_f32 v[52:53], v[58:59], v[178:179], v[64:65] op_sel_hi:[0,1,1]
	v_pk_fma_f32 v[48:49], v[58:59], v[180:181], v[66:67] op_sel_hi:[0,1,1]
	v_fma_f32 v61, v58, v188, v61
	ds_read_b32 v54, v97 offset:12160
	ds_read_b64 v[56:57], v98 offset:12224
	ds_write_b32 v99, v61 offset:3072
	s_waitcnt lgkmcnt(9)
	v_pk_mul_f32 v[58:59], v[52:53], v[194:195] op_sel_hi:[0,1]
	ds_read_b128 v[170:173], v96 offset:12496
	v_pk_fma_f32 v[58:59], v[52:53], v[196:197], v[58:59] op_sel:[1,0,0]
	ds_read_b128 v[174:177], v96 offset:12752
	v_pk_fma_f32 v[58:59], v[48:49], v[198:199], v[58:59] op_sel_hi:[0,1,1]
	v_pk_mul_f32 v[64:65], v[210:211], v[206:207] op_sel_hi:[0,1]
	v_pk_fma_f32 v[58:59], v[48:49], v[200:201], v[58:59] op_sel:[1,0,0]
	v_pk_mul_f32 v[66:67], v[210:211], v[208:209] op_sel_hi:[0,1]
	v_pk_fma_f32 v[64:65], v[52:53], v[190:191], v[64:65]
	v_add_f32_dpp v58, v58, v58 row_ror:8 row_mask:0xf bank_mask:0xf bound_ctrl:1
	v_pk_fma_f32 v[66:67], v[48:49], v[192:193], v[66:67]
	v_add_f32_dpp v60, v59, v59 row_ror:8 row_mask:0xf bank_mask:0xf bound_ctrl:1
	v_add_f32_dpp v58, v58, v58 row_ror:4 row_mask:0xf bank_mask:0xf bound_ctrl:1
	ds_read_b128 v[166:169], v96 offset:12240
	ds_read_b128 v[182:185], v96 offset:13264
	v_add_f32_dpp v58, v58, v58 row_ror:2 row_mask:0xf bank_mask:0xf bound_ctrl:1
	ds_read_b128 v[178:181], v96 offset:13008
	v_fma_f32 v61, v210, v221, v60
	v_add_f32_dpp v58, v58, v58 row_ror:1 row_mask:0xf bank_mask:0xf bound_ctrl:1
	v_pk_fma_f32 v[52:53], v[58:59], v[202:203], v[64:65] op_sel_hi:[0,1,1]
	v_pk_fma_f32 v[48:49], v[58:59], v[204:205], v[66:67] op_sel_hi:[0,1,1]
	v_fma_f32 v61, v58, v220, v61
	ds_read_b32 v186, v97 offset:13520
	ds_read_b64 v[188:189], v98 offset:13584
	ds_write_b32 v99, v61 offset:3584
	s_waitcnt lgkmcnt(9)
	v_pk_mul_f32 v[58:59], v[52:53], v[32:33] op_sel_hi:[0,1]
	ds_read_b128 v[194:197], v96 offset:13856
	v_pk_fma_f32 v[58:59], v[52:53], v[34:35], v[58:59] op_sel:[1,0,0]
	ds_read_b128 v[198:201], v96 offset:14112
	v_pk_fma_f32 v[58:59], v[48:49], v[36:37], v[58:59] op_sel_hi:[0,1,1]
	v_pk_mul_f32 v[64:65], v[54:55], v[44:45] op_sel_hi:[0,1]
	v_pk_fma_f32 v[58:59], v[48:49], v[38:39], v[58:59] op_sel:[1,0,0]
	v_pk_mul_f32 v[66:67], v[54:55], v[46:47] op_sel_hi:[0,1]
	v_pk_fma_f32 v[64:65], v[52:53], v[28:29], v[64:65]
	v_add_f32_dpp v58, v58, v58 row_ror:8 row_mask:0xf bank_mask:0xf bound_ctrl:1
	v_pk_fma_f32 v[66:67], v[48:49], v[30:31], v[66:67]
	v_add_f32_dpp v60, v59, v59 row_ror:8 row_mask:0xf bank_mask:0xf bound_ctrl:1
	v_add_f32_dpp v58, v58, v58 row_ror:4 row_mask:0xf bank_mask:0xf bound_ctrl:1
	ds_read_b128 v[190:193], v96 offset:13600
	ds_read_b128 v[206:209], v96 offset:14624
	v_add_f32_dpp v58, v58, v58 row_ror:2 row_mask:0xf bank_mask:0xf bound_ctrl:1
	ds_read_b128 v[202:205], v96 offset:14368
	v_fma_f32 v61, v54, v57, v60
	v_add_f32_dpp v58, v58, v58 row_ror:1 row_mask:0xf bank_mask:0xf bound_ctrl:1
	v_pk_fma_f32 v[52:53], v[58:59], v[40:41], v[64:65] op_sel_hi:[0,1,1]
	v_pk_fma_f32 v[48:49], v[58:59], v[42:43], v[66:67] op_sel_hi:[0,1,1]
	v_fma_f32 v61, v58, v56, v61
	ds_read_b32 v210, v97 offset:14880
	ds_read_b64 v[220:221], v98 offset:14944
	ds_write_b32 v99, v61 offset:4096
	s_waitcnt lgkmcnt(9)
	v_pk_mul_f32 v[58:59], v[52:53], v[170:171] op_sel_hi:[0,1]
	ds_read_b128 v[32:35], v96 offset:15216
	v_pk_fma_f32 v[58:59], v[52:53], v[172:173], v[58:59] op_sel:[1,0,0]
	ds_read_b128 v[36:39], v96 offset:15472
	v_pk_fma_f32 v[58:59], v[48:49], v[174:175], v[58:59] op_sel_hi:[0,1,1]
	v_pk_mul_f32 v[64:65], v[186:187], v[182:183] op_sel_hi:[0,1]
	v_pk_fma_f32 v[58:59], v[48:49], v[176:177], v[58:59] op_sel:[1,0,0]
	v_pk_mul_f32 v[66:67], v[186:187], v[184:185] op_sel_hi:[0,1]
	v_pk_fma_f32 v[64:65], v[52:53], v[166:167], v[64:65]
	v_add_f32_dpp v58, v58, v58 row_ror:8 row_mask:0xf bank_mask:0xf bound_ctrl:1
	v_pk_fma_f32 v[66:67], v[48:49], v[168:169], v[66:67]
	v_add_f32_dpp v60, v59, v59 row_ror:8 row_mask:0xf bank_mask:0xf bound_ctrl:1
	v_add_f32_dpp v58, v58, v58 row_ror:4 row_mask:0xf bank_mask:0xf bound_ctrl:1
	ds_read_b128 v[28:31], v96 offset:14960
	ds_read_b128 v[44:47], v96 offset:15984
	v_add_f32_dpp v58, v58, v58 row_ror:2 row_mask:0xf bank_mask:0xf bound_ctrl:1
	ds_read_b128 v[40:43], v96 offset:15728
	v_fma_f32 v61, v186, v189, v60
	v_add_f32_dpp v58, v58, v58 row_ror:1 row_mask:0xf bank_mask:0xf bound_ctrl:1
	v_pk_fma_f32 v[52:53], v[58:59], v[178:179], v[64:65] op_sel_hi:[0,1,1]
	v_pk_fma_f32 v[48:49], v[58:59], v[180:181], v[66:67] op_sel_hi:[0,1,1]
	v_fma_f32 v61, v58, v188, v61
	ds_read_b32 v54, v97 offset:16240
	ds_read_b64 v[56:57], v98 offset:16304
	ds_write_b32 v99, v61 offset:4608
	s_waitcnt lgkmcnt(9)
	v_pk_mul_f32 v[58:59], v[52:53], v[194:195] op_sel_hi:[0,1]
	ds_read_b128 v[170:173], v96 offset:16576
	v_pk_fma_f32 v[58:59], v[52:53], v[196:197], v[58:59] op_sel:[1,0,0]
	ds_read_b128 v[174:177], v96 offset:16832
	v_pk_fma_f32 v[58:59], v[48:49], v[198:199], v[58:59] op_sel_hi:[0,1,1]
	v_pk_mul_f32 v[64:65], v[210:211], v[206:207] op_sel_hi:[0,1]
	v_pk_fma_f32 v[58:59], v[48:49], v[200:201], v[58:59] op_sel:[1,0,0]
	v_pk_mul_f32 v[66:67], v[210:211], v[208:209] op_sel_hi:[0,1]
	v_pk_fma_f32 v[64:65], v[52:53], v[190:191], v[64:65]
	v_add_f32_dpp v58, v58, v58 row_ror:8 row_mask:0xf bank_mask:0xf bound_ctrl:1
	v_pk_fma_f32 v[66:67], v[48:49], v[192:193], v[66:67]
	v_add_f32_dpp v60, v59, v59 row_ror:8 row_mask:0xf bank_mask:0xf bound_ctrl:1
	v_add_f32_dpp v58, v58, v58 row_ror:4 row_mask:0xf bank_mask:0xf bound_ctrl:1
	ds_read_b128 v[166:169], v96 offset:16320
	ds_read_b128 v[182:185], v96 offset:17344
	v_add_f32_dpp v58, v58, v58 row_ror:2 row_mask:0xf bank_mask:0xf bound_ctrl:1
	ds_read_b128 v[178:181], v96 offset:17088
	v_fma_f32 v61, v210, v221, v60
	v_add_f32_dpp v58, v58, v58 row_ror:1 row_mask:0xf bank_mask:0xf bound_ctrl:1
	v_pk_fma_f32 v[52:53], v[58:59], v[202:203], v[64:65] op_sel_hi:[0,1,1]
	v_pk_fma_f32 v[48:49], v[58:59], v[204:205], v[66:67] op_sel_hi:[0,1,1]
	v_fma_f32 v61, v58, v220, v61
	ds_read_b32 v186, v97 offset:17600
	ds_read_b64 v[188:189], v98 offset:17664
	ds_write_b32 v99, v61 offset:5120
	s_waitcnt lgkmcnt(9)
	v_pk_mul_f32 v[58:59], v[52:53], v[32:33] op_sel_hi:[0,1]
	ds_read_b128 v[194:197], v96 offset:17936
	v_pk_fma_f32 v[58:59], v[52:53], v[34:35], v[58:59] op_sel:[1,0,0]
	ds_read_b128 v[198:201], v96 offset:18192
	v_pk_fma_f32 v[58:59], v[48:49], v[36:37], v[58:59] op_sel_hi:[0,1,1]
	v_pk_mul_f32 v[64:65], v[54:55], v[44:45] op_sel_hi:[0,1]
	v_pk_fma_f32 v[58:59], v[48:49], v[38:39], v[58:59] op_sel:[1,0,0]
	v_pk_mul_f32 v[66:67], v[54:55], v[46:47] op_sel_hi:[0,1]
	v_pk_fma_f32 v[64:65], v[52:53], v[28:29], v[64:65]
	v_add_f32_dpp v58, v58, v58 row_ror:8 row_mask:0xf bank_mask:0xf bound_ctrl:1
	v_pk_fma_f32 v[66:67], v[48:49], v[30:31], v[66:67]
	v_add_f32_dpp v60, v59, v59 row_ror:8 row_mask:0xf bank_mask:0xf bound_ctrl:1
	v_add_f32_dpp v58, v58, v58 row_ror:4 row_mask:0xf bank_mask:0xf bound_ctrl:1
	ds_read_b128 v[190:193], v96 offset:17680
	ds_read_b128 v[206:209], v96 offset:18704
	v_add_f32_dpp v58, v58, v58 row_ror:2 row_mask:0xf bank_mask:0xf bound_ctrl:1
	ds_read_b128 v[202:205], v96 offset:18448
	v_fma_f32 v61, v54, v57, v60
	v_add_f32_dpp v58, v58, v58 row_ror:1 row_mask:0xf bank_mask:0xf bound_ctrl:1
	v_pk_fma_f32 v[52:53], v[58:59], v[40:41], v[64:65] op_sel_hi:[0,1,1]
	v_pk_fma_f32 v[48:49], v[58:59], v[42:43], v[66:67] op_sel_hi:[0,1,1]
	v_fma_f32 v61, v58, v56, v61
	ds_read_b32 v210, v97 offset:18960
	ds_read_b64 v[220:221], v98 offset:19024
	ds_write_b32 v99, v61 offset:5632
	s_waitcnt lgkmcnt(9)
	v_pk_mul_f32 v[58:59], v[52:53], v[170:171] op_sel_hi:[0,1]
	ds_read_b128 v[32:35], v96 offset:19296
	v_pk_fma_f32 v[58:59], v[52:53], v[172:173], v[58:59] op_sel:[1,0,0]
	ds_read_b128 v[36:39], v96 offset:19552
	v_pk_fma_f32 v[58:59], v[48:49], v[174:175], v[58:59] op_sel_hi:[0,1,1]
	v_pk_mul_f32 v[64:65], v[186:187], v[182:183] op_sel_hi:[0,1]
	v_pk_fma_f32 v[58:59], v[48:49], v[176:177], v[58:59] op_sel:[1,0,0]
	v_pk_mul_f32 v[66:67], v[186:187], v[184:185] op_sel_hi:[0,1]
	v_pk_fma_f32 v[64:65], v[52:53], v[166:167], v[64:65]
	v_add_f32_dpp v58, v58, v58 row_ror:8 row_mask:0xf bank_mask:0xf bound_ctrl:1
	v_pk_fma_f32 v[66:67], v[48:49], v[168:169], v[66:67]
	v_add_f32_dpp v60, v59, v59 row_ror:8 row_mask:0xf bank_mask:0xf bound_ctrl:1
	v_add_f32_dpp v58, v58, v58 row_ror:4 row_mask:0xf bank_mask:0xf bound_ctrl:1
	ds_read_b128 v[28:31], v96 offset:19040
	ds_read_b128 v[44:47], v96 offset:20064
	v_add_f32_dpp v58, v58, v58 row_ror:2 row_mask:0xf bank_mask:0xf bound_ctrl:1
	ds_read_b128 v[40:43], v96 offset:19808
	v_fma_f32 v61, v186, v189, v60
	v_add_f32_dpp v58, v58, v58 row_ror:1 row_mask:0xf bank_mask:0xf bound_ctrl:1
	v_pk_fma_f32 v[52:53], v[58:59], v[178:179], v[64:65] op_sel_hi:[0,1,1]
	v_pk_fma_f32 v[48:49], v[58:59], v[180:181], v[66:67] op_sel_hi:[0,1,1]
	v_fma_f32 v61, v58, v188, v61
	ds_read_b32 v54, v97 offset:20320
	ds_read_b64 v[56:57], v98 offset:20384
	ds_write_b32 v99, v61 offset:6144
	s_waitcnt lgkmcnt(9)
	v_pk_mul_f32 v[58:59], v[52:53], v[194:195] op_sel_hi:[0,1]
	ds_read_b128 v[170:173], v96 offset:20656
	v_pk_fma_f32 v[58:59], v[52:53], v[196:197], v[58:59] op_sel:[1,0,0]
	ds_read_b128 v[174:177], v96 offset:20912
	v_pk_fma_f32 v[58:59], v[48:49], v[198:199], v[58:59] op_sel_hi:[0,1,1]
	v_pk_mul_f32 v[64:65], v[210:211], v[206:207] op_sel_hi:[0,1]
	v_pk_fma_f32 v[58:59], v[48:49], v[200:201], v[58:59] op_sel:[1,0,0]
	v_pk_mul_f32 v[66:67], v[210:211], v[208:209] op_sel_hi:[0,1]
	v_pk_fma_f32 v[64:65], v[52:53], v[190:191], v[64:65]
	v_add_f32_dpp v58, v58, v58 row_ror:8 row_mask:0xf bank_mask:0xf bound_ctrl:1
	v_pk_fma_f32 v[66:67], v[48:49], v[192:193], v[66:67]
	v_add_f32_dpp v60, v59, v59 row_ror:8 row_mask:0xf bank_mask:0xf bound_ctrl:1
	v_add_f32_dpp v58, v58, v58 row_ror:4 row_mask:0xf bank_mask:0xf bound_ctrl:1
	ds_read_b128 v[166:169], v96 offset:20400
	ds_read_b128 v[182:185], v96 offset:21424
	v_add_f32_dpp v58, v58, v58 row_ror:2 row_mask:0xf bank_mask:0xf bound_ctrl:1
	ds_read_b128 v[178:181], v96 offset:21168
	v_fma_f32 v61, v210, v221, v60
	v_add_f32_dpp v58, v58, v58 row_ror:1 row_mask:0xf bank_mask:0xf bound_ctrl:1
	v_pk_fma_f32 v[52:53], v[58:59], v[202:203], v[64:65] op_sel_hi:[0,1,1]
	v_pk_fma_f32 v[48:49], v[58:59], v[204:205], v[66:67] op_sel_hi:[0,1,1]
	v_fma_f32 v61, v58, v220, v61
	ds_read_b32 v186, v97 offset:21680
	ds_read_b64 v[188:189], v98 offset:21744
	ds_write_b32 v99, v61 offset:6656
	s_waitcnt lgkmcnt(9)
	v_pk_mul_f32 v[58:59], v[52:53], v[32:33] op_sel_hi:[0,1]
	ds_read_b128 v[194:197], v96 offset:22016
	v_pk_fma_f32 v[58:59], v[52:53], v[34:35], v[58:59] op_sel:[1,0,0]
	ds_read_b128 v[198:201], v96 offset:22272
	v_pk_fma_f32 v[58:59], v[48:49], v[36:37], v[58:59] op_sel_hi:[0,1,1]
	v_pk_mul_f32 v[64:65], v[54:55], v[44:45] op_sel_hi:[0,1]
	v_pk_fma_f32 v[58:59], v[48:49], v[38:39], v[58:59] op_sel:[1,0,0]
	v_pk_mul_f32 v[66:67], v[54:55], v[46:47] op_sel_hi:[0,1]
	v_pk_fma_f32 v[64:65], v[52:53], v[28:29], v[64:65]
	v_add_f32_dpp v58, v58, v58 row_ror:8 row_mask:0xf bank_mask:0xf bound_ctrl:1
	v_pk_fma_f32 v[66:67], v[48:49], v[30:31], v[66:67]
	v_add_f32_dpp v60, v59, v59 row_ror:8 row_mask:0xf bank_mask:0xf bound_ctrl:1
	v_add_f32_dpp v58, v58, v58 row_ror:4 row_mask:0xf bank_mask:0xf bound_ctrl:1
	ds_read_b128 v[190:193], v96 offset:21760
	ds_read_b128 v[206:209], v96 offset:22784
	v_add_f32_dpp v58, v58, v58 row_ror:2 row_mask:0xf bank_mask:0xf bound_ctrl:1
	ds_read_b128 v[202:205], v96 offset:22528
	v_fma_f32 v61, v54, v57, v60
	v_add_f32_dpp v58, v58, v58 row_ror:1 row_mask:0xf bank_mask:0xf bound_ctrl:1
	v_pk_fma_f32 v[52:53], v[58:59], v[40:41], v[64:65] op_sel_hi:[0,1,1]
	v_pk_fma_f32 v[48:49], v[58:59], v[42:43], v[66:67] op_sel_hi:[0,1,1]
	v_fma_f32 v61, v58, v56, v61
	ds_read_b32 v210, v97 offset:23040
	ds_read_b64 v[220:221], v98 offset:23104
	ds_write_b32 v99, v61 offset:7168
	s_waitcnt lgkmcnt(9)
	v_pk_mul_f32 v[58:59], v[52:53], v[170:171] op_sel_hi:[0,1]
	ds_read_b128 v[32:35], v96 offset:23376
	v_pk_fma_f32 v[58:59], v[52:53], v[172:173], v[58:59] op_sel:[1,0,0]
	ds_read_b128 v[36:39], v96 offset:23632
	v_pk_fma_f32 v[58:59], v[48:49], v[174:175], v[58:59] op_sel_hi:[0,1,1]
	v_pk_mul_f32 v[64:65], v[186:187], v[182:183] op_sel_hi:[0,1]
	v_pk_fma_f32 v[58:59], v[48:49], v[176:177], v[58:59] op_sel:[1,0,0]
	v_pk_mul_f32 v[66:67], v[186:187], v[184:185] op_sel_hi:[0,1]
	v_pk_fma_f32 v[64:65], v[52:53], v[166:167], v[64:65]
	v_add_f32_dpp v58, v58, v58 row_ror:8 row_mask:0xf bank_mask:0xf bound_ctrl:1
	v_pk_fma_f32 v[66:67], v[48:49], v[168:169], v[66:67]
	v_add_f32_dpp v60, v59, v59 row_ror:8 row_mask:0xf bank_mask:0xf bound_ctrl:1
	v_add_f32_dpp v58, v58, v58 row_ror:4 row_mask:0xf bank_mask:0xf bound_ctrl:1
	ds_read_b128 v[28:31], v96 offset:23120
	ds_read_b128 v[44:47], v96 offset:24144
	v_add_f32_dpp v58, v58, v58 row_ror:2 row_mask:0xf bank_mask:0xf bound_ctrl:1
	ds_read_b128 v[40:43], v96 offset:23888
	v_fma_f32 v61, v186, v189, v60
	v_add_f32_dpp v58, v58, v58 row_ror:1 row_mask:0xf bank_mask:0xf bound_ctrl:1
	v_pk_fma_f32 v[52:53], v[58:59], v[178:179], v[64:65] op_sel_hi:[0,1,1]
	v_pk_fma_f32 v[48:49], v[58:59], v[180:181], v[66:67] op_sel_hi:[0,1,1]
	v_fma_f32 v61, v58, v188, v61
	ds_read_b32 v54, v97 offset:24400
	ds_read_b64 v[56:57], v98 offset:24464
	ds_write_b32 v99, v61 offset:7680
	s_waitcnt lgkmcnt(9)
	v_pk_mul_f32 v[58:59], v[52:53], v[194:195] op_sel_hi:[0,1]
	ds_read_b128 v[170:173], v96 offset:24736
	v_pk_fma_f32 v[58:59], v[52:53], v[196:197], v[58:59] op_sel:[1,0,0]
	ds_read_b128 v[174:177], v96 offset:24992
	v_pk_fma_f32 v[58:59], v[48:49], v[198:199], v[58:59] op_sel_hi:[0,1,1]
	v_pk_mul_f32 v[64:65], v[210:211], v[206:207] op_sel_hi:[0,1]
	v_pk_fma_f32 v[58:59], v[48:49], v[200:201], v[58:59] op_sel:[1,0,0]
	v_pk_mul_f32 v[66:67], v[210:211], v[208:209] op_sel_hi:[0,1]
	v_pk_fma_f32 v[64:65], v[52:53], v[190:191], v[64:65]
	v_add_f32_dpp v58, v58, v58 row_ror:8 row_mask:0xf bank_mask:0xf bound_ctrl:1
	v_pk_fma_f32 v[66:67], v[48:49], v[192:193], v[66:67]
	v_add_f32_dpp v60, v59, v59 row_ror:8 row_mask:0xf bank_mask:0xf bound_ctrl:1
	v_add_f32_dpp v58, v58, v58 row_ror:4 row_mask:0xf bank_mask:0xf bound_ctrl:1
	ds_read_b128 v[166:169], v96 offset:24480
	ds_read_b128 v[182:185], v96 offset:25504
	v_add_f32_dpp v58, v58, v58 row_ror:2 row_mask:0xf bank_mask:0xf bound_ctrl:1
	ds_read_b128 v[178:181], v96 offset:25248
	v_fma_f32 v61, v210, v221, v60
	v_add_f32_dpp v58, v58, v58 row_ror:1 row_mask:0xf bank_mask:0xf bound_ctrl:1
	v_pk_fma_f32 v[52:53], v[58:59], v[202:203], v[64:65] op_sel_hi:[0,1,1]
	v_pk_fma_f32 v[48:49], v[58:59], v[204:205], v[66:67] op_sel_hi:[0,1,1]
	v_fma_f32 v61, v58, v220, v61
	ds_read_b32 v186, v97 offset:25760
	ds_read_b64 v[188:189], v98 offset:25824
	ds_write_b32 v99, v61 offset:8192
	s_waitcnt lgkmcnt(9)
	v_pk_mul_f32 v[58:59], v[52:53], v[32:33] op_sel_hi:[0,1]
	ds_read_b128 v[194:197], v96 offset:26096
	v_pk_fma_f32 v[58:59], v[52:53], v[34:35], v[58:59] op_sel:[1,0,0]
	ds_read_b128 v[198:201], v96 offset:26352
	v_pk_fma_f32 v[58:59], v[48:49], v[36:37], v[58:59] op_sel_hi:[0,1,1]
	v_pk_mul_f32 v[64:65], v[54:55], v[44:45] op_sel_hi:[0,1]
	v_pk_fma_f32 v[58:59], v[48:49], v[38:39], v[58:59] op_sel:[1,0,0]
	v_pk_mul_f32 v[66:67], v[54:55], v[46:47] op_sel_hi:[0,1]
	v_pk_fma_f32 v[64:65], v[52:53], v[28:29], v[64:65]
	v_add_f32_dpp v58, v58, v58 row_ror:8 row_mask:0xf bank_mask:0xf bound_ctrl:1
	v_pk_fma_f32 v[66:67], v[48:49], v[30:31], v[66:67]
	v_add_f32_dpp v60, v59, v59 row_ror:8 row_mask:0xf bank_mask:0xf bound_ctrl:1
	v_add_f32_dpp v58, v58, v58 row_ror:4 row_mask:0xf bank_mask:0xf bound_ctrl:1
	ds_read_b128 v[190:193], v96 offset:25840
	ds_read_b128 v[206:209], v96 offset:26864
	v_add_f32_dpp v58, v58, v58 row_ror:2 row_mask:0xf bank_mask:0xf bound_ctrl:1
	ds_read_b128 v[202:205], v96 offset:26608
	v_fma_f32 v61, v54, v57, v60
	v_add_f32_dpp v58, v58, v58 row_ror:1 row_mask:0xf bank_mask:0xf bound_ctrl:1
	v_pk_fma_f32 v[52:53], v[58:59], v[40:41], v[64:65] op_sel_hi:[0,1,1]
	v_pk_fma_f32 v[48:49], v[58:59], v[42:43], v[66:67] op_sel_hi:[0,1,1]
	v_fma_f32 v61, v58, v56, v61
	ds_read_b32 v210, v97 offset:27120
	ds_read_b64 v[220:221], v98 offset:27184
	ds_write_b32 v99, v61 offset:8704
	s_waitcnt lgkmcnt(9)
	v_pk_mul_f32 v[58:59], v[52:53], v[170:171] op_sel_hi:[0,1]
	ds_read_b128 v[32:35], v96 offset:27456
	v_pk_fma_f32 v[58:59], v[52:53], v[172:173], v[58:59] op_sel:[1,0,0]
	ds_read_b128 v[36:39], v96 offset:27712
	v_pk_fma_f32 v[58:59], v[48:49], v[174:175], v[58:59] op_sel_hi:[0,1,1]
	v_pk_mul_f32 v[64:65], v[186:187], v[182:183] op_sel_hi:[0,1]
	v_pk_fma_f32 v[58:59], v[48:49], v[176:177], v[58:59] op_sel:[1,0,0]
	v_pk_mul_f32 v[66:67], v[186:187], v[184:185] op_sel_hi:[0,1]
	v_pk_fma_f32 v[64:65], v[52:53], v[166:167], v[64:65]
	v_add_f32_dpp v58, v58, v58 row_ror:8 row_mask:0xf bank_mask:0xf bound_ctrl:1
	v_pk_fma_f32 v[66:67], v[48:49], v[168:169], v[66:67]
	v_add_f32_dpp v60, v59, v59 row_ror:8 row_mask:0xf bank_mask:0xf bound_ctrl:1
	v_add_f32_dpp v58, v58, v58 row_ror:4 row_mask:0xf bank_mask:0xf bound_ctrl:1
	ds_read_b128 v[28:31], v96 offset:27200
	ds_read_b128 v[44:47], v96 offset:28224
	v_add_f32_dpp v58, v58, v58 row_ror:2 row_mask:0xf bank_mask:0xf bound_ctrl:1
	ds_read_b128 v[40:43], v96 offset:27968
	v_fma_f32 v61, v186, v189, v60
	v_add_f32_dpp v58, v58, v58 row_ror:1 row_mask:0xf bank_mask:0xf bound_ctrl:1
	v_pk_fma_f32 v[52:53], v[58:59], v[178:179], v[64:65] op_sel_hi:[0,1,1]
	v_pk_fma_f32 v[48:49], v[58:59], v[180:181], v[66:67] op_sel_hi:[0,1,1]
	v_fma_f32 v61, v58, v188, v61
	ds_read_b32 v54, v97 offset:28480
	ds_read_b64 v[56:57], v98 offset:28544
	ds_write_b32 v99, v61 offset:9216
	s_waitcnt lgkmcnt(9)
	v_pk_mul_f32 v[58:59], v[52:53], v[194:195] op_sel_hi:[0,1]
	ds_read_b128 v[170:173], v96 offset:28816
	v_pk_fma_f32 v[58:59], v[52:53], v[196:197], v[58:59] op_sel:[1,0,0]
	ds_read_b128 v[174:177], v96 offset:29072
	v_pk_fma_f32 v[58:59], v[48:49], v[198:199], v[58:59] op_sel_hi:[0,1,1]
	v_pk_mul_f32 v[64:65], v[210:211], v[206:207] op_sel_hi:[0,1]
	v_pk_fma_f32 v[58:59], v[48:49], v[200:201], v[58:59] op_sel:[1,0,0]
	v_pk_mul_f32 v[66:67], v[210:211], v[208:209] op_sel_hi:[0,1]
	v_pk_fma_f32 v[64:65], v[52:53], v[190:191], v[64:65]
	v_add_f32_dpp v58, v58, v58 row_ror:8 row_mask:0xf bank_mask:0xf bound_ctrl:1
	v_pk_fma_f32 v[66:67], v[48:49], v[192:193], v[66:67]
	v_add_f32_dpp v60, v59, v59 row_ror:8 row_mask:0xf bank_mask:0xf bound_ctrl:1
	v_add_f32_dpp v58, v58, v58 row_ror:4 row_mask:0xf bank_mask:0xf bound_ctrl:1
	ds_read_b128 v[166:169], v96 offset:28560
	ds_read_b128 v[182:185], v96 offset:29584
	v_add_f32_dpp v58, v58, v58 row_ror:2 row_mask:0xf bank_mask:0xf bound_ctrl:1
	ds_read_b128 v[178:181], v96 offset:29328
	v_fma_f32 v61, v210, v221, v60
	v_add_f32_dpp v58, v58, v58 row_ror:1 row_mask:0xf bank_mask:0xf bound_ctrl:1
	v_pk_fma_f32 v[52:53], v[58:59], v[202:203], v[64:65] op_sel_hi:[0,1,1]
	v_pk_fma_f32 v[48:49], v[58:59], v[204:205], v[66:67] op_sel_hi:[0,1,1]
	v_fma_f32 v61, v58, v220, v61
	ds_read_b32 v186, v97 offset:29840
	ds_read_b64 v[188:189], v98 offset:29904
	ds_write_b32 v99, v61 offset:9728
	s_waitcnt lgkmcnt(9)
	v_pk_mul_f32 v[58:59], v[52:53], v[32:33] op_sel_hi:[0,1]
	ds_read_b128 v[194:197], v96 offset:30176
	v_pk_fma_f32 v[58:59], v[52:53], v[34:35], v[58:59] op_sel:[1,0,0]
	ds_read_b128 v[198:201], v96 offset:30432
	v_pk_fma_f32 v[58:59], v[48:49], v[36:37], v[58:59] op_sel_hi:[0,1,1]
	v_pk_mul_f32 v[64:65], v[54:55], v[44:45] op_sel_hi:[0,1]
	v_pk_fma_f32 v[58:59], v[48:49], v[38:39], v[58:59] op_sel:[1,0,0]
	v_pk_mul_f32 v[66:67], v[54:55], v[46:47] op_sel_hi:[0,1]
	v_pk_fma_f32 v[64:65], v[52:53], v[28:29], v[64:65]
	v_add_f32_dpp v58, v58, v58 row_ror:8 row_mask:0xf bank_mask:0xf bound_ctrl:1
	v_pk_fma_f32 v[66:67], v[48:49], v[30:31], v[66:67]
	v_add_f32_dpp v60, v59, v59 row_ror:8 row_mask:0xf bank_mask:0xf bound_ctrl:1
	v_add_f32_dpp v58, v58, v58 row_ror:4 row_mask:0xf bank_mask:0xf bound_ctrl:1
	ds_read_b128 v[190:193], v96 offset:29920
	ds_read_b128 v[206:209], v96 offset:30944
	v_add_f32_dpp v58, v58, v58 row_ror:2 row_mask:0xf bank_mask:0xf bound_ctrl:1
	ds_read_b128 v[202:205], v96 offset:30688
	v_fma_f32 v61, v54, v57, v60
	v_add_f32_dpp v58, v58, v58 row_ror:1 row_mask:0xf bank_mask:0xf bound_ctrl:1
	v_pk_fma_f32 v[52:53], v[58:59], v[40:41], v[64:65] op_sel_hi:[0,1,1]
	v_pk_fma_f32 v[48:49], v[58:59], v[42:43], v[66:67] op_sel_hi:[0,1,1]
	v_fma_f32 v61, v58, v56, v61
	ds_read_b32 v210, v97 offset:31200
	ds_read_b64 v[220:221], v98 offset:31264
	ds_write_b32 v99, v61 offset:10240
	s_waitcnt lgkmcnt(9)
	v_pk_mul_f32 v[58:59], v[52:53], v[170:171] op_sel_hi:[0,1]
	ds_read_b128 v[32:35], v96 offset:31536
	v_pk_fma_f32 v[58:59], v[52:53], v[172:173], v[58:59] op_sel:[1,0,0]
	ds_read_b128 v[36:39], v96 offset:31792
	v_pk_fma_f32 v[58:59], v[48:49], v[174:175], v[58:59] op_sel_hi:[0,1,1]
	v_pk_mul_f32 v[64:65], v[186:187], v[182:183] op_sel_hi:[0,1]
	v_pk_fma_f32 v[58:59], v[48:49], v[176:177], v[58:59] op_sel:[1,0,0]
	v_pk_mul_f32 v[66:67], v[186:187], v[184:185] op_sel_hi:[0,1]
	v_pk_fma_f32 v[64:65], v[52:53], v[166:167], v[64:65]
	v_add_f32_dpp v58, v58, v58 row_ror:8 row_mask:0xf bank_mask:0xf bound_ctrl:1
	v_pk_fma_f32 v[66:67], v[48:49], v[168:169], v[66:67]
	v_add_f32_dpp v60, v59, v59 row_ror:8 row_mask:0xf bank_mask:0xf bound_ctrl:1
	v_add_f32_dpp v58, v58, v58 row_ror:4 row_mask:0xf bank_mask:0xf bound_ctrl:1
	ds_read_b128 v[28:31], v96 offset:31280
	ds_read_b128 v[44:47], v96 offset:32304
	v_add_f32_dpp v58, v58, v58 row_ror:2 row_mask:0xf bank_mask:0xf bound_ctrl:1
	ds_read_b128 v[40:43], v96 offset:32048
	v_fma_f32 v61, v186, v189, v60
	v_add_f32_dpp v58, v58, v58 row_ror:1 row_mask:0xf bank_mask:0xf bound_ctrl:1
	v_pk_fma_f32 v[52:53], v[58:59], v[178:179], v[64:65] op_sel_hi:[0,1,1]
	v_pk_fma_f32 v[48:49], v[58:59], v[180:181], v[66:67] op_sel_hi:[0,1,1]
	v_fma_f32 v61, v58, v188, v61
	ds_read_b32 v54, v97 offset:32560
	ds_read_b64 v[56:57], v98 offset:32624
	ds_write_b32 v99, v61 offset:10752
	s_waitcnt lgkmcnt(9)
	v_pk_mul_f32 v[58:59], v[52:53], v[194:195] op_sel_hi:[0,1]
	ds_read_b128 v[170:173], v96 offset:32896
	v_pk_fma_f32 v[58:59], v[52:53], v[196:197], v[58:59] op_sel:[1,0,0]
	ds_read_b128 v[174:177], v96 offset:33152
	v_pk_fma_f32 v[58:59], v[48:49], v[198:199], v[58:59] op_sel_hi:[0,1,1]
	v_pk_mul_f32 v[64:65], v[210:211], v[206:207] op_sel_hi:[0,1]
	v_pk_fma_f32 v[58:59], v[48:49], v[200:201], v[58:59] op_sel:[1,0,0]
	v_pk_mul_f32 v[66:67], v[210:211], v[208:209] op_sel_hi:[0,1]
	v_pk_fma_f32 v[64:65], v[52:53], v[190:191], v[64:65]
	v_add_f32_dpp v58, v58, v58 row_ror:8 row_mask:0xf bank_mask:0xf bound_ctrl:1
	v_pk_fma_f32 v[66:67], v[48:49], v[192:193], v[66:67]
	v_add_f32_dpp v60, v59, v59 row_ror:8 row_mask:0xf bank_mask:0xf bound_ctrl:1
	v_add_f32_dpp v58, v58, v58 row_ror:4 row_mask:0xf bank_mask:0xf bound_ctrl:1
	ds_read_b128 v[166:169], v96 offset:32640
	ds_read_b128 v[182:185], v96 offset:33664
	v_add_f32_dpp v58, v58, v58 row_ror:2 row_mask:0xf bank_mask:0xf bound_ctrl:1
	ds_read_b128 v[178:181], v96 offset:33408
	v_fma_f32 v61, v210, v221, v60
	v_add_f32_dpp v58, v58, v58 row_ror:1 row_mask:0xf bank_mask:0xf bound_ctrl:1
	v_pk_fma_f32 v[52:53], v[58:59], v[202:203], v[64:65] op_sel_hi:[0,1,1]
	v_pk_fma_f32 v[48:49], v[58:59], v[204:205], v[66:67] op_sel_hi:[0,1,1]
	v_fma_f32 v61, v58, v220, v61
	ds_read_b32 v186, v97 offset:33920
	ds_read_b64 v[188:189], v98 offset:33984
	ds_write_b32 v99, v61 offset:11264
	s_waitcnt lgkmcnt(9)
	v_pk_mul_f32 v[58:59], v[52:53], v[32:33] op_sel_hi:[0,1]
	ds_read_b128 v[194:197], v96 offset:34256
	v_pk_fma_f32 v[58:59], v[52:53], v[34:35], v[58:59] op_sel:[1,0,0]
	ds_read_b128 v[198:201], v96 offset:34512
	v_pk_fma_f32 v[58:59], v[48:49], v[36:37], v[58:59] op_sel_hi:[0,1,1]
	v_pk_mul_f32 v[64:65], v[54:55], v[44:45] op_sel_hi:[0,1]
	v_pk_fma_f32 v[58:59], v[48:49], v[38:39], v[58:59] op_sel:[1,0,0]
	v_pk_mul_f32 v[66:67], v[54:55], v[46:47] op_sel_hi:[0,1]
	v_pk_fma_f32 v[64:65], v[52:53], v[28:29], v[64:65]
	v_add_f32_dpp v58, v58, v58 row_ror:8 row_mask:0xf bank_mask:0xf bound_ctrl:1
	v_pk_fma_f32 v[66:67], v[48:49], v[30:31], v[66:67]
	v_add_f32_dpp v60, v59, v59 row_ror:8 row_mask:0xf bank_mask:0xf bound_ctrl:1
	v_add_f32_dpp v58, v58, v58 row_ror:4 row_mask:0xf bank_mask:0xf bound_ctrl:1
	ds_read_b128 v[190:193], v96 offset:34000
	ds_read_b128 v[206:209], v96 offset:35024
	v_add_f32_dpp v58, v58, v58 row_ror:2 row_mask:0xf bank_mask:0xf bound_ctrl:1
	ds_read_b128 v[202:205], v96 offset:34768
	v_fma_f32 v61, v54, v57, v60
	v_add_f32_dpp v58, v58, v58 row_ror:1 row_mask:0xf bank_mask:0xf bound_ctrl:1
	v_pk_fma_f32 v[52:53], v[58:59], v[40:41], v[64:65] op_sel_hi:[0,1,1]
	v_pk_fma_f32 v[48:49], v[58:59], v[42:43], v[66:67] op_sel_hi:[0,1,1]
	v_fma_f32 v61, v58, v56, v61
	ds_read_b32 v210, v97 offset:35280
	ds_read_b64 v[220:221], v98 offset:35344
	ds_write_b32 v99, v61 offset:11776
	s_waitcnt lgkmcnt(9)
	v_pk_mul_f32 v[58:59], v[52:53], v[170:171] op_sel_hi:[0,1]
	ds_read_b128 v[32:35], v96 offset:35616
	v_pk_fma_f32 v[58:59], v[52:53], v[172:173], v[58:59] op_sel:[1,0,0]
	ds_read_b128 v[36:39], v96 offset:35872
	v_pk_fma_f32 v[58:59], v[48:49], v[174:175], v[58:59] op_sel_hi:[0,1,1]
	v_pk_mul_f32 v[64:65], v[186:187], v[182:183] op_sel_hi:[0,1]
	v_pk_fma_f32 v[58:59], v[48:49], v[176:177], v[58:59] op_sel:[1,0,0]
	v_pk_mul_f32 v[66:67], v[186:187], v[184:185] op_sel_hi:[0,1]
	v_pk_fma_f32 v[64:65], v[52:53], v[166:167], v[64:65]
	v_add_f32_dpp v58, v58, v58 row_ror:8 row_mask:0xf bank_mask:0xf bound_ctrl:1
	v_pk_fma_f32 v[66:67], v[48:49], v[168:169], v[66:67]
	v_add_f32_dpp v60, v59, v59 row_ror:8 row_mask:0xf bank_mask:0xf bound_ctrl:1
	v_add_f32_dpp v58, v58, v58 row_ror:4 row_mask:0xf bank_mask:0xf bound_ctrl:1
	ds_read_b128 v[28:31], v96 offset:35360
	ds_read_b128 v[44:47], v96 offset:36384
	v_add_f32_dpp v58, v58, v58 row_ror:2 row_mask:0xf bank_mask:0xf bound_ctrl:1
	ds_read_b128 v[40:43], v96 offset:36128
	v_fma_f32 v61, v186, v189, v60
	v_add_f32_dpp v58, v58, v58 row_ror:1 row_mask:0xf bank_mask:0xf bound_ctrl:1
	v_pk_fma_f32 v[52:53], v[58:59], v[178:179], v[64:65] op_sel_hi:[0,1,1]
	v_pk_fma_f32 v[48:49], v[58:59], v[180:181], v[66:67] op_sel_hi:[0,1,1]
	v_fma_f32 v61, v58, v188, v61
	ds_read_b32 v54, v97 offset:36640
	ds_read_b64 v[56:57], v98 offset:36704
	ds_write_b32 v99, v61 offset:12288
	s_waitcnt lgkmcnt(9)
	v_pk_mul_f32 v[58:59], v[52:53], v[194:195] op_sel_hi:[0,1]
	ds_read_b128 v[170:173], v96 offset:36976
	v_pk_fma_f32 v[58:59], v[52:53], v[196:197], v[58:59] op_sel:[1,0,0]
	ds_read_b128 v[174:177], v96 offset:37232
	v_pk_fma_f32 v[58:59], v[48:49], v[198:199], v[58:59] op_sel_hi:[0,1,1]
	v_pk_mul_f32 v[64:65], v[210:211], v[206:207] op_sel_hi:[0,1]
	v_pk_fma_f32 v[58:59], v[48:49], v[200:201], v[58:59] op_sel:[1,0,0]
	v_pk_mul_f32 v[66:67], v[210:211], v[208:209] op_sel_hi:[0,1]
	v_pk_fma_f32 v[64:65], v[52:53], v[190:191], v[64:65]
	v_add_f32_dpp v58, v58, v58 row_ror:8 row_mask:0xf bank_mask:0xf bound_ctrl:1
	v_pk_fma_f32 v[66:67], v[48:49], v[192:193], v[66:67]
	v_add_f32_dpp v60, v59, v59 row_ror:8 row_mask:0xf bank_mask:0xf bound_ctrl:1
	v_add_f32_dpp v58, v58, v58 row_ror:4 row_mask:0xf bank_mask:0xf bound_ctrl:1
	ds_read_b128 v[166:169], v96 offset:36720
	ds_read_b128 v[182:185], v96 offset:37744
	v_add_f32_dpp v58, v58, v58 row_ror:2 row_mask:0xf bank_mask:0xf bound_ctrl:1
	ds_read_b128 v[178:181], v96 offset:37488
	v_fma_f32 v61, v210, v221, v60
	v_add_f32_dpp v58, v58, v58 row_ror:1 row_mask:0xf bank_mask:0xf bound_ctrl:1
	v_pk_fma_f32 v[52:53], v[58:59], v[202:203], v[64:65] op_sel_hi:[0,1,1]
	v_pk_fma_f32 v[48:49], v[58:59], v[204:205], v[66:67] op_sel_hi:[0,1,1]
	v_fma_f32 v61, v58, v220, v61
	ds_read_b32 v186, v97 offset:38000
	ds_read_b64 v[188:189], v98 offset:38064
	ds_write_b32 v99, v61 offset:12800
	s_waitcnt lgkmcnt(9)
	v_pk_mul_f32 v[58:59], v[52:53], v[32:33] op_sel_hi:[0,1]
	ds_read_b128 v[194:197], v96 offset:38336
	v_pk_fma_f32 v[58:59], v[52:53], v[34:35], v[58:59] op_sel:[1,0,0]
	ds_read_b128 v[198:201], v96 offset:38592
	v_pk_fma_f32 v[58:59], v[48:49], v[36:37], v[58:59] op_sel_hi:[0,1,1]
	v_pk_mul_f32 v[64:65], v[54:55], v[44:45] op_sel_hi:[0,1]
	v_pk_fma_f32 v[58:59], v[48:49], v[38:39], v[58:59] op_sel:[1,0,0]
	v_pk_mul_f32 v[66:67], v[54:55], v[46:47] op_sel_hi:[0,1]
	v_pk_fma_f32 v[64:65], v[52:53], v[28:29], v[64:65]
	v_add_f32_dpp v58, v58, v58 row_ror:8 row_mask:0xf bank_mask:0xf bound_ctrl:1
	v_pk_fma_f32 v[66:67], v[48:49], v[30:31], v[66:67]
	v_add_f32_dpp v60, v59, v59 row_ror:8 row_mask:0xf bank_mask:0xf bound_ctrl:1
	v_add_f32_dpp v58, v58, v58 row_ror:4 row_mask:0xf bank_mask:0xf bound_ctrl:1
	ds_read_b128 v[190:193], v96 offset:38080
	ds_read_b128 v[206:209], v96 offset:39104
	v_add_f32_dpp v58, v58, v58 row_ror:2 row_mask:0xf bank_mask:0xf bound_ctrl:1
	ds_read_b128 v[202:205], v96 offset:38848
	v_fma_f32 v61, v54, v57, v60
	v_add_f32_dpp v58, v58, v58 row_ror:1 row_mask:0xf bank_mask:0xf bound_ctrl:1
	v_pk_fma_f32 v[52:53], v[58:59], v[40:41], v[64:65] op_sel_hi:[0,1,1]
	v_pk_fma_f32 v[48:49], v[58:59], v[42:43], v[66:67] op_sel_hi:[0,1,1]
	v_fma_f32 v61, v58, v56, v61
	ds_read_b32 v210, v97 offset:39360
	ds_read_b64 v[220:221], v98 offset:39424
	ds_write_b32 v99, v61 offset:13312
	s_waitcnt lgkmcnt(9)
	v_pk_mul_f32 v[58:59], v[52:53], v[170:171] op_sel_hi:[0,1]
	ds_read_b128 v[32:35], v96 offset:39696
	v_pk_fma_f32 v[58:59], v[52:53], v[172:173], v[58:59] op_sel:[1,0,0]
	ds_read_b128 v[36:39], v96 offset:39952
	v_pk_fma_f32 v[58:59], v[48:49], v[174:175], v[58:59] op_sel_hi:[0,1,1]
	v_pk_mul_f32 v[64:65], v[186:187], v[182:183] op_sel_hi:[0,1]
	v_pk_fma_f32 v[58:59], v[48:49], v[176:177], v[58:59] op_sel:[1,0,0]
	v_pk_mul_f32 v[66:67], v[186:187], v[184:185] op_sel_hi:[0,1]
	v_pk_fma_f32 v[64:65], v[52:53], v[166:167], v[64:65]
	v_add_f32_dpp v58, v58, v58 row_ror:8 row_mask:0xf bank_mask:0xf bound_ctrl:1
	v_pk_fma_f32 v[66:67], v[48:49], v[168:169], v[66:67]
	v_add_f32_dpp v60, v59, v59 row_ror:8 row_mask:0xf bank_mask:0xf bound_ctrl:1
	v_add_f32_dpp v58, v58, v58 row_ror:4 row_mask:0xf bank_mask:0xf bound_ctrl:1
	ds_read_b128 v[28:31], v96 offset:39440
	ds_read_b128 v[44:47], v96 offset:40464
	v_add_f32_dpp v58, v58, v58 row_ror:2 row_mask:0xf bank_mask:0xf bound_ctrl:1
	ds_read_b128 v[40:43], v96 offset:40208
	v_fma_f32 v61, v186, v189, v60
	v_add_f32_dpp v58, v58, v58 row_ror:1 row_mask:0xf bank_mask:0xf bound_ctrl:1
	v_pk_fma_f32 v[52:53], v[58:59], v[178:179], v[64:65] op_sel_hi:[0,1,1]
	v_pk_fma_f32 v[48:49], v[58:59], v[180:181], v[66:67] op_sel_hi:[0,1,1]
	v_fma_f32 v61, v58, v188, v61
	ds_read_b32 v54, v97 offset:40720
	ds_read_b64 v[56:57], v98 offset:40784
	ds_write_b32 v99, v61 offset:13824
	s_waitcnt lgkmcnt(9)
	v_pk_mul_f32 v[58:59], v[52:53], v[194:195] op_sel_hi:[0,1]
	ds_read_b128 v[170:173], v96 offset:41056
	v_pk_fma_f32 v[58:59], v[52:53], v[196:197], v[58:59] op_sel:[1,0,0]
	ds_read_b128 v[174:177], v96 offset:41312
	v_pk_fma_f32 v[58:59], v[48:49], v[198:199], v[58:59] op_sel_hi:[0,1,1]
	v_pk_mul_f32 v[64:65], v[210:211], v[206:207] op_sel_hi:[0,1]
	v_pk_fma_f32 v[58:59], v[48:49], v[200:201], v[58:59] op_sel:[1,0,0]
	v_pk_mul_f32 v[66:67], v[210:211], v[208:209] op_sel_hi:[0,1]
	v_pk_fma_f32 v[64:65], v[52:53], v[190:191], v[64:65]
	v_add_f32_dpp v58, v58, v58 row_ror:8 row_mask:0xf bank_mask:0xf bound_ctrl:1
	v_pk_fma_f32 v[66:67], v[48:49], v[192:193], v[66:67]
	v_add_f32_dpp v60, v59, v59 row_ror:8 row_mask:0xf bank_mask:0xf bound_ctrl:1
	v_add_f32_dpp v58, v58, v58 row_ror:4 row_mask:0xf bank_mask:0xf bound_ctrl:1
	ds_read_b128 v[166:169], v96 offset:40800
	ds_read_b128 v[182:185], v96 offset:41824
	v_add_f32_dpp v58, v58, v58 row_ror:2 row_mask:0xf bank_mask:0xf bound_ctrl:1
	ds_read_b128 v[178:181], v96 offset:41568
	v_fma_f32 v61, v210, v221, v60
	v_add_f32_dpp v58, v58, v58 row_ror:1 row_mask:0xf bank_mask:0xf bound_ctrl:1
	v_pk_fma_f32 v[52:53], v[58:59], v[202:203], v[64:65] op_sel_hi:[0,1,1]
	v_pk_fma_f32 v[48:49], v[58:59], v[204:205], v[66:67] op_sel_hi:[0,1,1]
	v_fma_f32 v61, v58, v220, v61
	ds_read_b32 v186, v97 offset:42080
	ds_read_b64 v[188:189], v98 offset:42144
	ds_write_b32 v99, v61 offset:14336
	s_waitcnt lgkmcnt(9)
	v_pk_mul_f32 v[58:59], v[52:53], v[32:33] op_sel_hi:[0,1]
	ds_read_b128 v[194:197], v96 offset:42416
	v_pk_fma_f32 v[58:59], v[52:53], v[34:35], v[58:59] op_sel:[1,0,0]
	ds_read_b128 v[198:201], v96 offset:42672
	v_pk_fma_f32 v[58:59], v[48:49], v[36:37], v[58:59] op_sel_hi:[0,1,1]
	v_pk_mul_f32 v[64:65], v[54:55], v[44:45] op_sel_hi:[0,1]
	v_pk_fma_f32 v[58:59], v[48:49], v[38:39], v[58:59] op_sel:[1,0,0]
	v_pk_mul_f32 v[66:67], v[54:55], v[46:47] op_sel_hi:[0,1]
	v_pk_fma_f32 v[64:65], v[52:53], v[28:29], v[64:65]
	v_add_f32_dpp v58, v58, v58 row_ror:8 row_mask:0xf bank_mask:0xf bound_ctrl:1
	v_pk_fma_f32 v[66:67], v[48:49], v[30:31], v[66:67]
	v_add_f32_dpp v60, v59, v59 row_ror:8 row_mask:0xf bank_mask:0xf bound_ctrl:1
	v_add_f32_dpp v58, v58, v58 row_ror:4 row_mask:0xf bank_mask:0xf bound_ctrl:1
	ds_read_b128 v[190:193], v96 offset:42160
	ds_read_b128 v[206:209], v96 offset:43184
	v_add_f32_dpp v58, v58, v58 row_ror:2 row_mask:0xf bank_mask:0xf bound_ctrl:1
	ds_read_b128 v[202:205], v96 offset:42928
	v_fma_f32 v61, v54, v57, v60
	v_add_f32_dpp v58, v58, v58 row_ror:1 row_mask:0xf bank_mask:0xf bound_ctrl:1
	v_pk_fma_f32 v[52:53], v[58:59], v[40:41], v[64:65] op_sel_hi:[0,1,1]
	v_pk_fma_f32 v[48:49], v[58:59], v[42:43], v[66:67] op_sel_hi:[0,1,1]
	v_fma_f32 v61, v58, v56, v61
	ds_read_b32 v210, v97 offset:43440
	ds_read_b64 v[220:221], v98 offset:43504
	ds_write_b32 v99, v61 offset:14848
	s_waitcnt lgkmcnt(9)
	v_pk_mul_f32 v[58:59], v[52:53], v[170:171] op_sel_hi:[0,1]
	v_pk_fma_f32 v[58:59], v[52:53], v[172:173], v[58:59] op_sel:[1,0,0]
	v_pk_fma_f32 v[58:59], v[48:49], v[174:175], v[58:59] op_sel_hi:[0,1,1]
	v_pk_mul_f32 v[64:65], v[186:187], v[182:183] op_sel_hi:[0,1]
	v_pk_fma_f32 v[58:59], v[48:49], v[176:177], v[58:59] op_sel:[1,0,0]
	v_pk_mul_f32 v[66:67], v[186:187], v[184:185] op_sel_hi:[0,1]
	v_pk_fma_f32 v[64:65], v[52:53], v[166:167], v[64:65]
	v_add_f32_dpp v58, v58, v58 row_ror:8 row_mask:0xf bank_mask:0xf bound_ctrl:1
	v_pk_fma_f32 v[66:67], v[48:49], v[168:169], v[66:67]
	v_add_f32_dpp v60, v59, v59 row_ror:8 row_mask:0xf bank_mask:0xf bound_ctrl:1
	v_add_f32_dpp v58, v58, v58 row_ror:4 row_mask:0xf bank_mask:0xf bound_ctrl:1
	s_nop 1
	v_add_f32_dpp v58, v58, v58 row_ror:2 row_mask:0xf bank_mask:0xf bound_ctrl:1
	s_nop 0
	v_fma_f32 v61, v186, v189, v60
	v_add_f32_dpp v58, v58, v58 row_ror:1 row_mask:0xf bank_mask:0xf bound_ctrl:1
	v_pk_fma_f32 v[52:53], v[58:59], v[178:179], v[64:65] op_sel_hi:[0,1,1]
	v_pk_fma_f32 v[48:49], v[58:59], v[180:181], v[66:67] op_sel_hi:[0,1,1]
	v_fma_f32 v61, v58, v188, v61
	ds_write_b32 v99, v61 offset:15360
	s_waitcnt lgkmcnt(2)
	v_pk_mul_f32 v[58:59], v[52:53], v[194:195] op_sel_hi:[0,1]
	v_pk_fma_f32 v[58:59], v[52:53], v[196:197], v[58:59] op_sel:[1,0,0]
	v_pk_fma_f32 v[58:59], v[48:49], v[198:199], v[58:59] op_sel_hi:[0,1,1]
	v_pk_mul_f32 v[64:65], v[210:211], v[206:207] op_sel_hi:[0,1]
	v_pk_fma_f32 v[58:59], v[48:49], v[200:201], v[58:59] op_sel:[1,0,0]
	v_pk_mul_f32 v[66:67], v[210:211], v[208:209] op_sel_hi:[0,1]
	v_pk_fma_f32 v[64:65], v[52:53], v[190:191], v[64:65]
	v_add_f32_dpp v58, v58, v58 row_ror:8 row_mask:0xf bank_mask:0xf bound_ctrl:1
	v_pk_fma_f32 v[66:67], v[48:49], v[192:193], v[66:67]
	v_add_f32_dpp v60, v59, v59 row_ror:8 row_mask:0xf bank_mask:0xf bound_ctrl:1
	v_add_f32_dpp v58, v58, v58 row_ror:4 row_mask:0xf bank_mask:0xf bound_ctrl:1
	s_nop 1
	v_add_f32_dpp v58, v58, v58 row_ror:2 row_mask:0xf bank_mask:0xf bound_ctrl:1
	s_nop 0
	v_fma_f32 v61, v210, v221, v60
	v_add_f32_dpp v58, v58, v58 row_ror:1 row_mask:0xf bank_mask:0xf bound_ctrl:1
	v_pk_fma_f32 v[52:53], v[58:59], v[202:203], v[64:65] op_sel_hi:[0,1,1]
	v_pk_fma_f32 v[48:49], v[58:59], v[204:205], v[66:67] op_sel_hi:[0,1,1]
	v_fma_f32 v61, v58, v220, v61
	ds_write_b32 v99, v61 offset:15872
	s_setprio 0
	s_mov_b64 s[78:79], 0
